# de-serialized unit prologues in both HGRN passes and pool epilogue, DPP row reduce in HGRN norm, attention DMA at step top
# speedup vs baseline: 1.0091x; 1.0091x over previous
; #define LAS __attribute__((address_space(3)))
; __device__ __forceinline__ unsigned pk2(float lo, float hi) { f32x2_t v = {lo, hi}; bf16x2_t b = __builtin_convertvector(v, bf16x2_t); return __builtin_bit_cast(unsigned, b); }
; template <bool PC> __device__ __forceinline__ void hgrn_unit(LAS unsigned char* lds, int unit, const bf16* P0, const float* lbp, const float* ong, float* Lst, const float* Sst, float* Dtot, bf16* MIX) {
;     int tid = threadIdx.x; asm volatile("" : "+v"(tid)); const int lane = tid & 63, wave = tid >> 6, li = lane & 15, g = lane >> 4, q4 = li >> 2, p4 = li & 3;
;     const int b = unit >> 7, hd = (unit >> 5) & 3, sc = unit & 31;
;     const int row0 = b * SEQL + sc * 256;
;     const int k = 16 * wave + li, tq = g;
;     float lb;
;     { const float a0 = lbp[hd * 128 + k], a1 = lbp[512 + hd * 128 + k], a2 = lbp[1024 + hd * 128 + k]; const float mx = fmaxf(a0, fmaxf(a1, a2));
;       const float e0 = __expf(a0 - mx), e1 = __expf(a1 - mx), e2 = __expf(a2 - mx); lb = e0 / (e0 + e1 + e2); }
;     f32x4 S[8];
;     if (PC) {
; #pragma unroll
;         for (int kb = 0; kb < 8; ++kb) { S[kb] = *(const f32x4*)(Sst + (size_t)unit * 16384 + (16 * kb + li) * 128 + 16 * wave + 4 * g);
;             *(LAS v2u*)(lds + HL_S + (16 * kb + li) * RS + (16 * wave + 4 * g) * 2) = (v2u){pk2(S[kb][0], S[kb][1]), pk2(S[kb][2], S[kb][3])}; }
;     } else {
; #pragma unroll
;         for (int kb = 0; kb < 8; ++kb) S[kb] = (f32x4){0.f, 0.f, 0.f, 0.f};
;     }
;     float sumlog = 0.f;
;     f32x4 g0 = (f32x4){0.f, 0.f, 0.f, 0.f}, g1 = g0; if (PC) { g0 = *(const f32x4*)(ong + hd * 128 + 8 * (tid & 15)); g1 = *(const f32x4*)(ong + hd * 128 + 8 * (tid & 15) + 4); }
;     LAS float* DEC = (LAS float*)(lds + HL_DEC);
;     unsigned nf[8], nq[8]; v4u nv, ng = (v4u){0u, 0u, 0u, 0u};
;     ...
;     HG_LOAD(0);
.LBB0_219:
	v_mov_b32_e32 v18, v216
	s_lshl_b32 s5, s42, 2
	v_ashrrev_i32_e32 v4, 2, v18
	v_bfi_b32 v44, -16, v4, v18
	s_and_b32 s14, s5, 0x180
	v_add_u32_e32 v0, s14, v44
	v_ashrrev_i32_e32 v1, 31, v0
	v_lshl_add_u64 v[2:3], v[0:1], 2, s[78:79]
	v_add_u32_e32 v0, 0x400, v0
	v_ashrrev_i32_e32 v1, 31, v0
	v_lshl_add_u64 v[0:1], v[0:1], 2, s[78:79]
	global_load_dword v17, v[2:3], off
	global_load_dword v19, v[2:3], off offset:2048
	global_load_dword v20, v[0:1], off
	s_lshl_b32 s15, s42, 6
	s_lshl_b32 s17, s42, 8
	s_and_b32 s17, s17, 0x1f00
	s_and_b32 s15, s15, 0xffffe000
	v_bfe_u32 v21, v18, 4, 2
	s_or_b32 s15, s15, s17
	v_ashrrev_i32_e32 v23, 4, v18
	v_lshlrev_b32_e32 v24, 3, v21
	v_add_u32_e32 v0, s15, v23
	v_or_b32_e32 v2, s15, v24
	v_and_b32_e32 v61, 15, v18
	s_lshl_b32 s22, s14, 1
	v_ashrrev_i32_e32 v45, 31, v44
	v_mad_i64_i32 v[0:1], s[14:15], v0, s74, v[40:41]
	v_mad_i64_i32 v[2:3], s[14:15], v2, s74, v[40:41]
	v_and_b32_e32 v46, -16, v4
	v_lshlrev_b32_e32 v42, 4, v61
	v_lshlrev_b64 v[4:5], 1, v[44:45]
	v_lshl_add_u64 v[0:1], v[0:1], 0, s[22:23]
	v_lshl_add_u64 v[2:3], v[2:3], 0, s[22:23]
	s_movk_i32 s18, 0x1000
	v_lshl_add_u64 v[0:1], v[0:1], 0, v[42:43]
	v_lshl_add_u64 v[2:3], v[2:3], 0, v[4:5]
	global_load_dwordx4 v[32:35], v[0:1], off offset:2048
	v_add_co_u32_e32 v0, vcc, s18, v2
	s_movk_i32 s19, 0x3000
	s_nop 0
	v_addc_co_u32_e32 v1, vcc, 0, v3, vcc
	v_add_co_u32_e32 v6, vcc, s19, v2
	s_and_b32 s5, s50, 0xffffe000
	s_nop 0
	v_addc_co_u32_e32 v7, vcc, 0, v3, vcc
	v_add_co_u32_e32 v8, vcc, s75, v2
	s_and_b32 s16, s70, 0x1f00
	s_nop 0
	v_addc_co_u32_e32 v9, vcc, 0, v3, vcc
	v_add_co_u32_e32 v10, vcc, s76, v2
	v_bfe_u32 v22, v18, 2, 2
	s_nop 0
	v_addc_co_u32_e32 v11, vcc, 0, v3, vcc
	v_add_co_u32_e32 v12, vcc, s24, v2
	v_mul_lo_u32 v25, v23, s77
	s_nop 0
	v_addc_co_u32_e32 v13, vcc, 0, v3, vcc
	v_add_co_u32_e32 v14, vcc, s25, v2
	v_lshlrev_b32_e32 v52, 4, v21
	s_nop 0
	v_addc_co_u32_e32 v15, vcc, 0, v3, vcc
	v_add_co_u32_e32 v16, vcc, 0xa000, v2
	v_cmp_eq_u32_e64 s[36:37], 0, v21
	v_cmp_lt_u32_e64 s[38:39], 1, v21
	v_cmp_eq_u32_e64 s[40:41], 3, v21
	v_lshl_add_u32 v66, v61, 2, 0
	v_mov_b32_e32 v45, 0
	v_mov_b32_e32 v21, v43
	v_mov_b32_e32 v28, 0
	v_mov_b32_e32 v29, v43
	v_mov_b32_e32 v30, v43
	v_mov_b32_e32 v31, v43
	v_mov_b32_e32 v122, v16
	v_addc_co_u32_e32 v123, vcc, 0, v3, vcc
	global_load_ushort v86, v[2:3], off offset:1024
	global_load_ushort v87, v[0:1], off offset:3072
	global_load_ushort v85, v[6:7], off offset:1024
	global_load_ushort v84, v[8:9], off offset:3072
	global_load_ushort v83, v[10:11], off offset:1024
	global_load_ushort v80, v[12:13], off offset:3072
	global_load_ushort v81, v[14:15], off offset:1024
	global_load_ushort v82, v[122:123], off offset:3072
	s_waitcnt vmcnt(9)
	v_max3_f32 v26, v17, v19, v20
	v_sub_f32_e32 v17, v17, v26
	v_mul_f32_e32 v17, 0x3fb8aa3b, v17
	v_sub_f32_e32 v19, v19, v26
	v_sub_f32_e32 v20, v20, v26
	v_exp_f32_e32 v26, v17
	v_mul_f32_e32 v19, 0x3fb8aa3b, v19
	v_mul_f32_e32 v20, 0x3fb8aa3b, v20
	v_exp_f32_e32 v19, v19
	v_exp_f32_e32 v20, v20
	v_lshlrev_b32_e32 v3, 2, v18
	v_and_or_b32 v3, v3, 12, v46
	v_add_f32_e32 v19, v26, v19
	v_add_f32_e32 v19, v20, v19
	v_div_scale_f32 v20, s[14:15], v19, v19, v26
	v_rcp_f32_e32 v27, v20
	v_div_scale_f32 v0, vcc, v26, v19, v26
	s_movk_i32 s14, 0x50
	v_fma_f32 v1, -v20, v27, 1.0
	v_fmac_f32_e32 v27, v1, v27
	v_mul_f32_e32 v1, v0, v27
	v_fma_f32 v2, -v20, v1, v0
	v_fmac_f32_e32 v1, v2, v27
	v_fma_f32 v0, -v20, v1, v0
	v_div_fmas_f32 v0, v0, v27, v1
	v_cmp_lt_i32_e32 vcc, v58, v217
	v_div_fixup_f32 v48, v0, v19, v26
	v_or_b32_e32 v2, v24, v22
	v_cndmask_b32_e32 v1, v58, v208, vcc
	v_cmp_lt_i32_e32 vcc, v59, v217
	v_lshlrev_b32_e32 v47, 2, v1
	v_sub_f32_e32 v50, 1.0, v48
	v_cndmask_b32_e32 v1, v59, v208, vcc
	v_cmp_lt_i32_e32 vcc, v60, v217
	v_lshlrev_b32_e32 v53, 2, v1
	v_add_u32_e32 v0, 0, v25
	v_cndmask_b32_e32 v1, v60, v208, vcc
	v_cmp_lt_i32_e32 vcc, v211, v209
	v_lshlrev_b32_e32 v62, 2, v1
	v_mad_u32_u24 v2, v2, s77, 0
	v_cndmask_b32_e32 v1, v208, v211, vcc
	v_cmp_lt_i32_e32 vcc, v210, v209
	v_lshlrev_b32_e32 v63, 2, v1
	v_lshlrev_b32_e32 v3, 1, v3
	v_cndmask_b32_e32 v1, v208, v210, vcc
	v_lshlrev_b32_e32 v64, 2, v1
	v_mul_lo_u32 v1, v44, s14
	s_movk_i32 s14, 0xffb4
	v_add_u32_e32 v65, 0, v1
	v_mul_lo_u32 v1, v44, s14
	s_add_u32 s14, s20, s22
	v_add_u32_e32 v6, 0, v52
	v_mul_u32_u24_e32 v7, 0x50, v61
	s_addc_u32 s15, s21, 0
	s_or_b32 s5, s5, s16
	s_waitcnt vmcnt(8)
	v_mov_b64_e32 v[38:39], v[34:35]
	v_mov_b32_e32 v49, v48
	v_mov_b32_e32 v51, v50
	v_lshl_add_u64 v[54:55], s[14:15], 0, v[4:5]
	v_lshl_add_u64 v[56:57], s[14:15], 0, v[42:43]
	v_add3_u32 v67, v23, s5, 32
	v_or3_b32 v68, v24, s5, 32
	v_add_u32_e32 v42, v0, v42
	v_add_u32_e32 v69, v65, v1
	v_add_u32_e32 v70, v2, v3
	v_add_u32_e32 v71, v6, v7
	s_mov_b32 s5, 0
	v_mov_b32_e32 v24, 0
	v_mov_b32_e32 v25, v43
	v_mov_b32_e32 v26, v43
	v_mov_b32_e32 v27, v43
	v_mov_b32_e32 v16, 0
	v_mov_b32_e32 v17, v43
	v_mov_b32_e32 v18, v43
	v_mov_b32_e32 v19, v43
	v_mov_b32_e32 v20, 0
	v_mov_b32_e32 v22, v43
	v_mov_b32_e32 v23, v43
	v_mov_b32_e32 v12, 0
	v_mov_b32_e32 v13, v43
	v_mov_b32_e32 v14, v43
	v_mov_b32_e32 v15, v43
	v_mov_b32_e32 v4, 0
	v_mov_b32_e32 v5, v43
	v_mov_b32_e32 v6, v43
	v_mov_b32_e32 v7, v43
	v_mov_b32_e32 v8, 0
	v_mov_b32_e32 v9, v43
	v_mov_b32_e32 v10, v43
	v_mov_b32_e32 v11, v43
	v_mov_b32_e32 v0, 0
	v_mov_b32_e32 v1, v43
	v_mov_b32_e32 v2, v43
	v_mov_b32_e32 v3, v43
	s_waitcnt vmcnt(7)
	v_mov_b32_e32 v72, v86
	s_waitcnt vmcnt(6)
	v_mov_b32_e32 v73, v87
	s_waitcnt vmcnt(5)
	v_mov_b32_e32 v74, v85
	s_waitcnt vmcnt(4)
	v_mov_b32_e32 v75, v84
	s_waitcnt vmcnt(3)
	v_mov_b32_e32 v76, v83
	s_waitcnt vmcnt(2)
	v_mov_b32_e32 v77, v80
	s_waitcnt vmcnt(1)
	v_mov_b32_e32 v78, v81
	s_waitcnt vmcnt(0)
	v_mov_b32_e32 v79, v82
	v_mov_b64_e32 v[36:37], v[32:33]
	s_cmpk_lg_i32 s5, 0xe0
	s_cbranch_scc0 .LBB0_222
	s_branch .LBB0_221

; #define LAS __attribute__((address_space(3)))
; __device__ __forceinline__ unsigned pk2(float lo, float hi) { f32x2_t v = {lo, hi}; bf16x2_t b = __builtin_convertvector(v, bf16x2_t); return __builtin_bit_cast(unsigned, b); }
; __device__ __forceinline__ float bflo(unsigned w) { return __uint_as_float(w << 16); }
; __device__ __forceinline__ float bfhi(unsigned w) { return __uint_as_float(w & 0xffff0000u); }
; template <int W> __device__ __forceinline__ void pool_fill(LAS unsigned char* Al, const LAS unsigned char* Ul, int tid, int tt0) {
;     ...
;         for (int j = 0; j < W; ++j) { const v4u x = *(const LAS v4u*)(Ul + (t + 15 - j) * RS + (cq * 32 + ch * 8) * 2); if (j == 0) self = x;
; #pragma unroll
;             for (int e = 0; e < 4; ++e) { acc[2 * e] += bflo(x[e]); acc[2 * e + 1] += bfhi(x[e]); } }
;         v4u o;
; #pragma unroll
;         for (int e = 0; e < 4; ++e) o[e] = pk2(acc[2 * e] * inv - bflo(self[e]), acc[2 * e + 1] * inv - bfhi(self[e]));
;         *(LAS v4u*)(Al + t * RS + (cq * 32 + ch * 8) * 2) = o;
; __device__ __forceinline__ void pool_unit(LAS unsigned char* lds, int unit, const bf16* P0, const bf16* PWt, const float* pscale, bf16* MIX) {
;     ...
;     f32x4 acc[8];
; #pragma unroll
;     for (int db = 0; db < 8; ++db) acc[db] = (f32x4){0.f, 0.f, 0.f, 0.f};
; #pragma unroll
;     for (int ks = 0; ks < 4; ++ks) {
;         const bf16x8 y = *(const LAS bf16x8*)(Al + (16 * wave + li) * RS + (32 * ks + 8 * g) * 2);
; #pragma unroll
;         for (int db = 0; db < 8; ++db) { const bf16x8 x = *(const LAS bf16x8*)(Bl + (16 * db + li) * RS + (32 * ks + 8 * g) * 2);
;             acc[db] = __builtin_amdgcn_mfma_f32_16x16x32_bf16(x, y, acc[db], 0, 0, 0); }
;     }
;     const int row = row0 + 16 * wave + li;
;     v2u gbv[8]; f32x4 psv[8];
; #pragma unroll
;     for (int db = 0; db < 8; ++db) { const int dcol = grp * 128 + 16 * db + 4 * g; gbv[db] = *(const v2u*)(P0 + (size_t)row * N0 + 2560 + dcol); psv[db] = *(const f32x4*)(pscale + dcol); }
.LBB0_230:
	ds_read_b128 v[6:9], v68
	v_mov_b32_e32 v49, v48
	v_bfe_u32 v90, v92, 4, 2
	v_and_b32_e32 v91, 15, v92
	s_add_i32 s75, s75, s6
	s_waitcnt lgkmcnt(0)
	v_lshlrev_b32_e32 v10, 16, v6
	v_and_b32_e32 v11, 0xffff0000, v6
	v_lshlrev_b32_e32 v12, 16, v7
	v_and_b32_e32 v13, 0xffff0000, v7
	v_pk_add_f32 v[6:7], v[84:85], v[10:11]
	v_pk_add_f32 v[0:1], v[0:1], v[12:13]
	v_pk_fma_f32 v[6:7], v[48:49], v[6:7], v[44:45] neg_lo:[0,0,1] neg_hi:[0,0,1]
	v_pk_fma_f32 v[0:1], v[48:49], v[0:1], v[46:47] neg_lo:[0,0,1] neg_hi:[0,0,1]
	v_cvt_pk_bf16_f32 v6, v6, v7
	v_cvt_pk_bf16_f32 v7, v0, v1
	v_lshlrev_b32_e32 v0, 16, v8
	v_and_b32_e32 v1, 0xffff0000, v8
	v_pk_add_f32 v[0:1], v[4:5], v[0:1]
	s_add_i32 s18, s18, s19
	v_pk_fma_f32 v[0:1], v[48:49], v[0:1], v[32:33] neg_lo:[0,0,1] neg_hi:[0,0,1]
	s_cmpk_gt_i32 s75, 0x1ff
	v_cvt_pk_bf16_f32 v8, v0, v1
	v_lshlrev_b32_e32 v0, 16, v9
	v_and_b32_e32 v1, 0xffff0000, v9
	v_pk_add_f32 v[0:1], v[2:3], v[0:1]
	s_nop 0
	v_pk_fma_f32 v[0:1], v[48:49], v[0:1], v[36:37] neg_lo:[0,0,1] neg_hi:[0,0,1]
	s_nop 0
	v_cvt_pk_bf16_f32 v9, v0, v1
	v_add_u32_e32 v0, v94, v93
	ds_write_b128 v0, v[6:9] offset:48
	v_lshl_add_u32 v0, v90, 4, 0
	v_mad_u32_u24 v86, v91, s71, v0
	s_waitcnt lgkmcnt(0)
	s_barrier
	ds_read_b128 v[2:5], v86 offset:34816
	v_bfi_b32 v1, -16, v56, v92
	v_mad_u64_u32 v[0:1], s[0:1], v1, s71, v[0:1]
	ds_read_b128 v[6:9], v0
	ds_read_b128 v[10:13], v0 offset:64
	ds_read_b128 v[14:17], v86 offset:34880
	ds_read_b128 v[18:21], v86 offset:39168
	ds_read_b128 v[22:25], v86 offset:39232
	ds_read_b128 v[26:29], v86 offset:43520
	ds_read_b128 v[30:33], v86 offset:43584
	ds_read_b128 v[34:37], v86 offset:47872
	ds_read_b128 v[38:41], v86 offset:47936
	s_waitcnt lgkmcnt(8)
	v_mfma_f32_16x16x32_bf16 v[2:5], v[2:5], v[6:9], 0
	ds_read_b128 v[42:45], v86 offset:52224
	ds_read_b128 v[46:49], v86 offset:52288
	ds_read_b128 v[50:53], v86 offset:56576
	ds_read_b128 v[58:61], v86 offset:56640
	ds_read_b128 v[62:65], v86 offset:60928
	ds_read_b128 v[66:69], v86 offset:60992
	s_waitcnt lgkmcnt(11)
	v_mfma_f32_16x16x32_bf16 v[18:21], v[18:21], v[6:9], 0
	ds_read_b128 v[70:73], v86 offset:65280
	ds_read_b128 v[74:77], v86 offset:65344
	s_waitcnt lgkmcnt(9)
	v_mfma_f32_16x16x32_bf16 v[34:37], v[34:37], v[6:9], 0
	v_mfma_f32_16x16x32_bf16 v[2:5], v[14:17], v[10:13], v[2:5]
	v_mfma_f32_16x16x32_bf16 v[14:17], v[22:25], v[10:13], v[18:21]
	s_waitcnt lgkmcnt(8)
	v_mfma_f32_16x16x32_bf16 v[22:25], v[38:41], v[10:13], v[34:37]
	ds_read_b128 v[38:41], v86 offset:34944
	v_mfma_f32_16x16x32_bf16 v[26:29], v[26:29], v[6:9], 0
	s_waitcnt lgkmcnt(8)
	v_mfma_f32_16x16x32_bf16 v[42:45], v[42:45], v[6:9], 0
	s_waitcnt lgkmcnt(6)
	v_mfma_f32_16x16x32_bf16 v[50:53], v[50:53], v[6:9], 0
	s_waitcnt lgkmcnt(4)
	v_mfma_f32_16x16x32_bf16 v[62:65], v[62:65], v[6:9], 0
	s_waitcnt lgkmcnt(2)
	v_mfma_f32_16x16x32_bf16 v[6:9], v[70:73], v[6:9], 0
	v_mfma_f32_16x16x32_bf16 v[18:21], v[30:33], v[10:13], v[26:29]
	v_mfma_f32_16x16x32_bf16 v[26:29], v[46:49], v[10:13], v[42:45]
	v_mfma_f32_16x16x32_bf16 v[30:33], v[58:61], v[10:13], v[50:53]
	v_mfma_f32_16x16x32_bf16 v[34:37], v[66:69], v[10:13], v[62:65]
	s_waitcnt lgkmcnt(1)
	v_mfma_f32_16x16x32_bf16 v[6:9], v[74:77], v[10:13], v[6:9]
	ds_read_b128 v[10:13], v0 offset:128
	ds_read_b128 v[44:47], v0 offset:192
	ds_read_b128 v[48:51], v86 offset:35008
	s_waitcnt lgkmcnt(2)
	v_mfma_f32_16x16x32_bf16 v[0:3], v[38:41], v[10:13], v[2:5]
	ds_read_b128 v[38:41], v86 offset:39296
	ds_read_b128 v[52:55], v86 offset:39360
	s_waitcnt lgkmcnt(1)
	v_mfma_f32_16x16x32_bf16 v[14:17], v[38:41], v[10:13], v[14:17]
	ds_read_b128 v[38:41], v86 offset:43648
	ds_read_b128 v[58:61], v86 offset:43712
	s_waitcnt lgkmcnt(1)
	v_mfma_f32_16x16x32_bf16 v[18:21], v[38:41], v[10:13], v[18:21]
	ds_read_b128 v[38:41], v86 offset:48000
	ds_read_b128 v[62:65], v86 offset:48064
	s_waitcnt lgkmcnt(1)
	v_mfma_f32_16x16x32_bf16 v[22:25], v[38:41], v[10:13], v[22:25]
	ds_read_b128 v[38:41], v86 offset:52352
	ds_read_b128 v[66:69], v86 offset:52416
	s_waitcnt lgkmcnt(1)
	v_mfma_f32_16x16x32_bf16 v[26:29], v[38:41], v[10:13], v[26:29]
	ds_read_b128 v[38:41], v86 offset:56704
	ds_read_b128 v[74:77], v86 offset:56768
	s_waitcnt lgkmcnt(1)
	v_mfma_f32_16x16x32_bf16 v[78:81], v[38:41], v[10:13], v[30:33]
	s_nop 2
	ds_read_b128 v[30:33], v86 offset:61056
	ds_read_b128 v[82:85], v86 offset:61120
	s_waitcnt lgkmcnt(1)
	v_mfma_f32_16x16x32_bf16 v[36:39], v[30:33], v[10:13], v[34:37]
	ds_read_b128 v[30:33], v86 offset:65408
	ds_read_b128 v[86:89], v86 offset:65472
	s_nop 0
	v_and_b32_e32 v34, -16, v56
	s_waitcnt lgkmcnt(1)
	v_mfma_f32_16x16x32_bf16 v[4:7], v[30:33], v[10:13], v[6:9]
	s_nop 2
	v_add_u32_e32 v8, s76, v34
	v_or_b32_e32 v98, v8, v91
	v_lshl_or_b32 v8, v90, 2, s77
	v_mfma_f32_16x16x32_bf16 v[90:93], v[48:51], v[44:47], v[0:3]
	v_lshlrev_b32_e32 v56, 1, v8
	v_lshlrev_b32_e32 v100, 2, v8
	global_load_dwordx4 v[94:97], v100, s[54:55]
	v_mov_b64_e32 v[0:1], s[20:21]
	v_mad_i64_i32 v[0:1], s[0:1], v98, s70, v[0:1]
	s_mov_b64 s[0:1], 0x1400
	s_nop 0
	v_lshl_add_u64 v[12:13], v[0:1], 0, s[0:1]
	v_lshl_add_u64 v[0:1], v[12:13], 0, v[56:57]
	v_mfma_f32_16x16x32_bf16 v[40:43], v[58:61], v[44:47], v[18:21]
	global_load_dwordx2 v[60:61], v[0:1], off
	v_or_b32_e32 v0, 32, v56
	v_mov_b32_e32 v1, v57
	v_lshl_add_u64 v[0:1], v[12:13], 0, v[0:1]
	global_load_dwordx2 v[72:73], v[0:1], off
	v_mfma_f32_16x16x32_bf16 v[48:51], v[52:55], v[44:47], v[14:17]
	global_load_dwordx4 v[52:55], v100, s[54:55] offset:64
	v_lshl_add_u64 v[118:119], v[12:13], 0, v[56:57]
	global_load_dwordx4 v[120:123], v100, s[54:55] offset:128
	global_load_dwordx4 v[124:127], v100, s[54:55] offset:192
	global_load_dwordx2 v[144:145], v[118:119], off offset:64
	global_load_dwordx2 v[146:147], v[118:119], off offset:96
	global_load_dwordx2 v[148:149], v[118:119], off offset:128
	global_load_dwordx4 v[128:131], v100, s[54:55] offset:256
	global_load_dwordx4 v[132:135], v100, s[54:55] offset:320
	global_load_dwordx2 v[150:151], v[118:119], off offset:160
	global_load_dwordx2 v[152:153], v[118:119], off offset:192
	global_load_dwordx2 v[154:155], v[118:119], off offset:224
	global_load_dwordx4 v[136:139], v100, s[54:55] offset:384
	global_load_dwordx4 v[140:143], v100, s[54:55] offset:448
	v_or_b32_e32 v0, 64, v56
	v_mov_b32_e32 v1, v57
	v_lshl_add_u64 v[14:15], v[12:13], 0, v[0:1]
	v_or_b32_e32 v20, 0x60, v56
	s_waitcnt lgkmcnt(0)
; __device__ __forceinline__ unsigned pk2(float lo, float hi) { f32x2_t v = {lo, hi}; bf16x2_t b = __builtin_convertvector(v, bf16x2_t); return __builtin_bit_cast(unsigned, b); }
; __device__ __forceinline__ float bflo(unsigned w) { return __uint_as_float(w << 16); }
; __device__ __forceinline__ float bfhi(unsigned w) { return __uint_as_float(w & 0xffff0000u); }
; __device__ __forceinline__ float siluf(float x) { return x * sigmf(x); }
; __device__ __forceinline__ void pool_unit(LAS unsigned char* lds, int unit, const bf16* P0, const bf16* PWt, const float* pscale, bf16* MIX) {
;     ...
;     const int row = row0 + 16 * wave + li;
;     v2u gbv[8]; f32x4 psv[8];
; #pragma unroll
;     for (int db = 0; db < 8; ++db) { const int dcol = grp * 128 + 16 * db + 4 * g; gbv[db] = *(const v2u*)(P0 + (size_t)row * N0 + 2560 + dcol); psv[db] = *(const f32x4*)(pscale + dcol); }
; #pragma unroll
;     for (int db = 0; db < 8; ++db) { const int dcol = grp * 128 + 16 * db + 4 * g;
;         const v2u gb = gbv[db]; const f32x4 ps = psv[db];
;         const float o0 = acc[db][0] * ps[0] * siluf(bflo(gb[0])), o1 = acc[db][1] * ps[1] * siluf(bfhi(gb[0])), o2 = acc[db][2] * ps[2] * siluf(bflo(gb[1])), o3 = acc[db][3] * ps[3] * siluf(bfhi(gb[1]));
;         *(v2u*)(MIX + (size_t)row * D + 512 + dcol) = (v2u){pk2(o0, o1), pk2(o2, o3)}; }
	v_mfma_f32_16x16x32_bf16 v[0:3], v[86:89], v[44:47], v[4:7]
	v_mov_b32_e32 v21, v57
	v_ashrrev_i32_e32 v99, 31, v98
	s_waitcnt vmcnt(0)
	v_pk_mul_f32 v[50:51], v[50:51], v[54:55]
	v_or_b32_e32 v6, 0x80, v56
	v_mov_b32_e32 v7, v57
	v_mfma_f32_16x16x32_bf16 v[32:35], v[62:65], v[44:47], v[22:25]
	v_lshl_add_u64 v[4:5], v[12:13], 0, v[20:21]
	v_lshl_add_u64 v[6:7], v[12:13], 0, v[6:7]
	v_lshlrev_b32_e32 v54, 16, v73
	v_mfma_f32_16x16x32_bf16 v[24:27], v[66:69], v[44:47], v[26:29]
	v_and_b32_e32 v55, 0xffff0000, v73
	v_mul_f32_e32 v73, 0xbfb8aa3b, v54
	v_pk_mul_f32 v[48:49], v[48:49], v[52:53]
	v_mfma_f32_16x16x32_bf16 v[16:19], v[74:77], v[44:47], v[78:81]
	v_lshlrev_b32_e32 v76, 16, v60
	v_mul_f32_e32 v77, 0xbfb8aa3b, v76
	v_lshlrev_b64 v[74:75], 11, v[98:99]
	v_mfma_f32_16x16x32_bf16 v[8:11], v[82:85], v[44:47], v[36:39]
	v_mov_b64_e32 v[44:45], v[120:121]
	v_mov_b64_e32 v[46:47], v[122:123]
	s_nop 1
	v_mov_b64_e32 v[36:37], v[124:125]
	v_mov_b64_e32 v[38:39], v[126:127]
	v_mov_b64_e32 v[70:71], v[144:145]
	v_mov_b64_e32 v[68:69], v[146:147]
	v_mov_b64_e32 v[66:67], v[148:149]
	v_mov_b64_e32 v[28:29], v[128:129]
	v_mov_b64_e32 v[30:31], v[130:131]
	v_mov_b64_e32 v[20:21], v[132:133]
	v_mov_b64_e32 v[22:23], v[134:135]
	v_exp_f32_e32 v78, v77
	v_and_b32_e32 v77, 0xffff0000, v60
	v_mul_f32_e32 v60, 0xbfb8aa3b, v77
	v_exp_f32_e32 v80, v60
	v_and_b32_e32 v81, 0xffff0000, v61
	v_or_b32_e32 v4, 0xa0, v56
	v_mov_b32_e32 v5, v57
	v_add_f32_e32 v82, 1.0, v80
	v_lshlrev_b32_e32 v80, 16, v61
	v_mul_f32_e32 v61, 0xbfb8aa3b, v80
	v_exp_f32_e32 v83, v61
	v_mul_f32_e32 v61, 0xbfb8aa3b, v81
	v_exp_f32_e32 v84, v61
	v_or_b32_e32 v6, 0xc0, v56
	v_mov_b32_e32 v7, v57
	v_or_b32_e32 v14, 0xe0, v56
	v_mov_b32_e32 v15, v57
	v_add_f32_e32 v60, 1.0, v78
	v_lshl_add_u64 v[4:5], v[12:13], 0, v[4:5]
	v_lshl_add_u64 v[6:7], v[12:13], 0, v[6:7]
	v_lshl_add_u64 v[12:13], v[12:13], 0, v[14:15]
	v_rcp_f32_e32 v60, v60
	v_rcp_f32_e32 v61, v82
	v_add_f32_e32 v82, 1.0, v83
	v_add_f32_e32 v83, 1.0, v84
	v_mov_b64_e32 v[64:65], v[150:151]
	v_mov_b64_e32 v[62:63], v[152:153]
	v_mov_b64_e32 v[58:59], v[154:155]
	s_nop 0
	v_mov_b64_e32 v[12:13], v[136:137]
	v_mov_b64_e32 v[14:15], v[138:139]
	v_mov_b64_e32 v[4:5], v[140:141]
	v_mov_b64_e32 v[6:7], v[142:143]
	v_rcp_f32_e32 v82, v82
	v_rcp_f32_e32 v83, v83
	v_pk_mul_f32 v[84:85], v[90:91], v[94:95]
	v_pk_mul_f32 v[60:61], v[60:61], v[76:77]
	v_lshl_add_u64 v[74:75], s[2:3], 0, v[74:75]
	v_pk_mul_f32 v[78:79], v[92:93], v[96:97]
	v_pk_mul_f32 v[60:61], v[84:85], v[60:61]
	v_pk_mul_f32 v[76:77], v[82:83], v[80:81]
	s_waitcnt vmcnt(11)
	v_pk_mul_f32 v[42:43], v[42:43], v[46:47]
	v_pk_mul_f32 v[76:77], v[78:79], v[76:77]
	v_cvt_pk_bf16_f32 v78, v60, v61
	v_lshl_add_u64 v[60:61], v[74:75], 0, v[56:57]
	v_lshlrev_b32_e32 v74, 16, v72
	v_mul_f32_e32 v56, 0xbfb8aa3b, v74
	v_and_b32_e32 v75, 0xffff0000, v72
	v_exp_f32_e32 v56, v56
	v_mul_f32_e32 v72, 0xbfb8aa3b, v75
	v_cvt_pk_bf16_f32 v79, v76, v77
	v_exp_f32_e32 v76, v72
	v_add_f32_e32 v56, 1.0, v56
	v_rcp_f32_e32 v72, v56
	s_waitcnt vmcnt(9)
	v_lshlrev_b32_e32 v46, 16, v71
	v_add_f32_e32 v56, 1.0, v76
	v_exp_f32_e32 v76, v73
	v_mul_f32_e32 v73, 0xbfb8aa3b, v55
	v_exp_f32_e32 v77, v73
	v_rcp_f32_e32 v73, v56
	v_add_f32_e32 v56, 1.0, v76
	v_rcp_f32_e32 v76, v56
	v_add_f32_e32 v56, 1.0, v77
	v_rcp_f32_e32 v77, v56
	v_pk_mul_f32 v[52:53], v[72:73], v[74:75]
	v_and_b32_e32 v47, 0xffff0000, v71
	v_pk_mul_f32 v[48:49], v[48:49], v[52:53]
	v_pk_mul_f32 v[52:53], v[76:77], v[54:55]
	v_cvt_pk_bf16_f32 v48, v48, v49
	v_pk_mul_f32 v[50:51], v[50:51], v[52:53]
	v_mul_f32_e32 v52, 0xbfb8aa3b, v46
	v_cvt_pk_bf16_f32 v49, v50, v51
	global_store_dwordx2 v[60:61], v[48:49], off offset:1056
	v_lshlrev_b32_e32 v48, 16, v70
	v_mul_f32_e32 v49, 0xbfb8aa3b, v48
	v_exp_f32_e32 v50, v49
	v_and_b32_e32 v49, 0xffff0000, v70
	v_mul_f32_e32 v51, 0xbfb8aa3b, v49
	v_exp_f32_e32 v51, v51
	v_mul_f32_e32 v53, 0xbfb8aa3b, v47
	v_exp_f32_e32 v52, v52
	v_exp_f32_e32 v53, v53
	v_add_f32_e32 v50, 1.0, v50
	v_add_f32_e32 v51, 1.0, v51
	v_rcp_f32_e32 v50, v50
	v_rcp_f32_e32 v51, v51
	v_add_f32_e32 v52, 1.0, v52
	v_add_f32_e32 v53, 1.0, v53
	v_rcp_f32_e32 v52, v52
	v_rcp_f32_e32 v53, v53
	v_pk_mul_f32 v[40:41], v[40:41], v[44:45]
	v_pk_mul_f32 v[44:45], v[50:51], v[48:49]
	v_pk_mul_f32 v[34:35], v[34:35], v[38:39]
	v_pk_mul_f32 v[40:41], v[40:41], v[44:45]
	v_pk_mul_f32 v[44:45], v[52:53], v[46:47]
	v_cvt_pk_bf16_f32 v40, v40, v41
	v_pk_mul_f32 v[42:43], v[42:43], v[44:45]
	s_waitcnt vmcnt(9)
; __device__ __forceinline__ unsigned pk2(float lo, float hi) { f32x2_t v = {lo, hi}; bf16x2_t b = __builtin_convertvector(v, bf16x2_t); return __builtin_bit_cast(unsigned, b); }
; __device__ __forceinline__ float bflo(unsigned w) { return __uint_as_float(w << 16); }
; __device__ __forceinline__ float bfhi(unsigned w) { return __uint_as_float(w & 0xffff0000u); }
; __device__ __forceinline__ float siluf(float x) { return x * sigmf(x); }
; __device__ __forceinline__ void pool_unit(LAS unsigned char* lds, int unit, const bf16* P0, const bf16* PWt, const float* pscale, bf16* MIX) {
;     ...
;     for (int db = 0; db < 8; ++db) { const int dcol = grp * 128 + 16 * db + 4 * g;
;         const v2u gb = gbv[db]; const f32x4 ps = psv[db];
;         const float o0 = acc[db][0] * ps[0] * siluf(bflo(gb[0])), o1 = acc[db][1] * ps[1] * siluf(bfhi(gb[0])), o2 = acc[db][2] * ps[2] * siluf(bflo(gb[1])), o3 = acc[db][3] * ps[3] * siluf(bfhi(gb[1]));
;         *(v2u*)(MIX + (size_t)row * D + 512 + dcol) = (v2u){pk2(o0, o1), pk2(o2, o3)}; }
;     __syncthreads();
	v_lshlrev_b32_e32 v38, 16, v69
	v_cvt_pk_bf16_f32 v41, v42, v43
	global_store_dwordx2 v[60:61], v[40:41], off offset:1088
	v_lshlrev_b32_e32 v40, 16, v68
	v_mul_f32_e32 v41, 0xbfb8aa3b, v40
	v_exp_f32_e32 v42, v41
	v_and_b32_e32 v41, 0xffff0000, v68
	v_mul_f32_e32 v43, 0xbfb8aa3b, v41
	v_and_b32_e32 v39, 0xffff0000, v69
	v_exp_f32_e32 v43, v43
	v_mul_f32_e32 v44, 0xbfb8aa3b, v38
	v_mul_f32_e32 v45, 0xbfb8aa3b, v39
	v_exp_f32_e32 v44, v44
	v_exp_f32_e32 v45, v45
	v_add_f32_e32 v42, 1.0, v42
	v_add_f32_e32 v43, 1.0, v43
	v_rcp_f32_e32 v42, v42
	v_rcp_f32_e32 v43, v43
	v_add_f32_e32 v44, 1.0, v44
	v_add_f32_e32 v45, 1.0, v45
	v_rcp_f32_e32 v44, v44
	v_rcp_f32_e32 v45, v45
	v_pk_mul_f32 v[32:33], v[32:33], v[36:37]
	v_pk_mul_f32 v[36:37], v[42:43], v[40:41]
	s_waitcnt vmcnt(8)
	v_pk_mul_f32 v[26:27], v[26:27], v[30:31]
	v_pk_mul_f32 v[32:33], v[32:33], v[36:37]
	v_pk_mul_f32 v[36:37], v[44:45], v[38:39]
	v_cvt_pk_bf16_f32 v32, v32, v33
	v_pk_mul_f32 v[34:35], v[34:35], v[36:37]
	v_lshlrev_b32_e32 v30, 16, v67
	v_cvt_pk_bf16_f32 v33, v34, v35
	global_store_dwordx2 v[60:61], v[32:33], off offset:1120
	v_lshlrev_b32_e32 v32, 16, v66
	v_mul_f32_e32 v33, 0xbfb8aa3b, v32
	v_exp_f32_e32 v34, v33
	v_and_b32_e32 v33, 0xffff0000, v66
	v_mul_f32_e32 v35, 0xbfb8aa3b, v33
	v_and_b32_e32 v31, 0xffff0000, v67
	v_exp_f32_e32 v35, v35
	v_mul_f32_e32 v36, 0xbfb8aa3b, v30
	v_mul_f32_e32 v37, 0xbfb8aa3b, v31
	v_exp_f32_e32 v36, v36
	v_exp_f32_e32 v37, v37
	v_add_f32_e32 v34, 1.0, v34
	v_add_f32_e32 v35, 1.0, v35
	v_rcp_f32_e32 v34, v34
	v_rcp_f32_e32 v35, v35
	v_add_f32_e32 v36, 1.0, v36
	v_add_f32_e32 v37, 1.0, v37
	v_rcp_f32_e32 v36, v36
	v_rcp_f32_e32 v37, v37
	v_pk_mul_f32 v[24:25], v[24:25], v[28:29]
	v_pk_mul_f32 v[28:29], v[34:35], v[32:33]
	s_waitcnt vmcnt(8)
	v_pk_mul_f32 v[18:19], v[18:19], v[22:23]
	v_pk_mul_f32 v[24:25], v[24:25], v[28:29]
	v_pk_mul_f32 v[28:29], v[36:37], v[30:31]
	v_cvt_pk_bf16_f32 v24, v24, v25
	v_pk_mul_f32 v[26:27], v[26:27], v[28:29]
	s_waitcnt vmcnt(7)
	v_lshlrev_b32_e32 v22, 16, v65
	v_cvt_pk_bf16_f32 v25, v26, v27
	global_store_dwordx2 v[60:61], v[24:25], off offset:1152
	v_lshlrev_b32_e32 v24, 16, v64
	v_mul_f32_e32 v25, 0xbfb8aa3b, v24
	v_exp_f32_e32 v26, v25
	v_and_b32_e32 v25, 0xffff0000, v64
	v_mul_f32_e32 v27, 0xbfb8aa3b, v25
	v_and_b32_e32 v23, 0xffff0000, v65
	v_exp_f32_e32 v27, v27
	v_mul_f32_e32 v28, 0xbfb8aa3b, v22
	v_mul_f32_e32 v29, 0xbfb8aa3b, v23
	v_exp_f32_e32 v28, v28
	v_exp_f32_e32 v29, v29
	v_add_f32_e32 v26, 1.0, v26
	v_add_f32_e32 v27, 1.0, v27
	v_rcp_f32_e32 v26, v26
	v_rcp_f32_e32 v27, v27
	v_add_f32_e32 v28, 1.0, v28
	v_add_f32_e32 v29, 1.0, v29
	v_rcp_f32_e32 v28, v28
	v_rcp_f32_e32 v29, v29
	v_pk_mul_f32 v[16:17], v[16:17], v[20:21]
	v_pk_mul_f32 v[20:21], v[26:27], v[24:25]
	s_waitcnt vmcnt(5)
	v_pk_mul_f32 v[10:11], v[10:11], v[14:15]
	v_pk_mul_f32 v[16:17], v[16:17], v[20:21]
	v_pk_mul_f32 v[20:21], v[28:29], v[22:23]
	v_cvt_pk_bf16_f32 v16, v16, v17
	v_pk_mul_f32 v[18:19], v[18:19], v[20:21]
	v_lshlrev_b32_e32 v14, 16, v63
	v_cvt_pk_bf16_f32 v17, v18, v19
	global_store_dwordx2 v[60:61], v[16:17], off offset:1184
	v_lshlrev_b32_e32 v16, 16, v62
	v_mul_f32_e32 v17, 0xbfb8aa3b, v16
	v_exp_f32_e32 v18, v17
	v_and_b32_e32 v17, 0xffff0000, v62
	v_mul_f32_e32 v19, 0xbfb8aa3b, v17
	v_and_b32_e32 v15, 0xffff0000, v63
	v_exp_f32_e32 v19, v19
	v_mul_f32_e32 v20, 0xbfb8aa3b, v14
	v_mul_f32_e32 v21, 0xbfb8aa3b, v15
	v_exp_f32_e32 v20, v20
	v_exp_f32_e32 v21, v21
	v_add_f32_e32 v18, 1.0, v18
	v_add_f32_e32 v19, 1.0, v19
	v_rcp_f32_e32 v18, v18
	v_rcp_f32_e32 v19, v19
	v_add_f32_e32 v20, 1.0, v20
	v_add_f32_e32 v21, 1.0, v21
	v_rcp_f32_e32 v20, v20
	v_rcp_f32_e32 v21, v21
	v_pk_mul_f32 v[8:9], v[8:9], v[12:13]
	v_pk_mul_f32 v[12:13], v[18:19], v[16:17]
	s_waitcnt vmcnt(5)
	v_pk_mul_f32 v[2:3], v[2:3], v[6:7]
	v_pk_mul_f32 v[8:9], v[8:9], v[12:13]
	v_pk_mul_f32 v[12:13], v[20:21], v[14:15]
	v_cvt_pk_bf16_f32 v8, v8, v9
	v_pk_mul_f32 v[10:11], v[10:11], v[12:13]
	v_lshlrev_b32_e32 v6, 16, v59
	v_cvt_pk_bf16_f32 v9, v10, v11
	global_store_dwordx2 v[60:61], v[8:9], off offset:1216
	v_lshlrev_b32_e32 v8, 16, v58
	v_mul_f32_e32 v9, 0xbfb8aa3b, v8
	v_exp_f32_e32 v10, v9
	v_and_b32_e32 v9, 0xffff0000, v58
	v_mul_f32_e32 v11, 0xbfb8aa3b, v9
	v_and_b32_e32 v7, 0xffff0000, v59
	v_exp_f32_e32 v11, v11
	v_mul_f32_e32 v12, 0xbfb8aa3b, v6
	v_mul_f32_e32 v13, 0xbfb8aa3b, v7
	v_exp_f32_e32 v12, v12
	v_exp_f32_e32 v13, v13
	v_add_f32_e32 v10, 1.0, v10
	v_add_f32_e32 v11, 1.0, v11
	v_rcp_f32_e32 v10, v10
	v_rcp_f32_e32 v11, v11
	v_add_f32_e32 v12, 1.0, v12
	v_add_f32_e32 v13, 1.0, v13
	v_rcp_f32_e32 v12, v12
	v_rcp_f32_e32 v13, v13
	v_pk_mul_f32 v[0:1], v[0:1], v[4:5]
	v_pk_mul_f32 v[4:5], v[10:11], v[8:9]
	global_store_dwordx2 v[60:61], v[78:79], off offset:1024
	v_pk_mul_f32 v[0:1], v[0:1], v[4:5]
	v_pk_mul_f32 v[4:5], v[12:13], v[6:7]
	v_cvt_pk_bf16_f32 v0, v0, v1
	v_pk_mul_f32 v[2:3], v[2:3], v[4:5]
	s_nop 0
	v_cvt_pk_bf16_f32 v1, v2, v3
	global_store_dwordx2 v[60:61], v[0:1], off offset:1248
	s_barrier
	s_cbranch_scc1 .LBB0_261

; #define LAS __attribute__((address_space(3)))
; __device__ __forceinline__ unsigned pk2(float lo, float hi) { f32x2_t v = {lo, hi}; bf16x2_t b = __builtin_convertvector(v, bf16x2_t); return __builtin_bit_cast(unsigned, b); }
; template <bool PC> __device__ __forceinline__ void hgrn_unit(LAS unsigned char* lds, int unit, const bf16* P0, const float* lbp, const float* ong, float* Lst, const float* Sst, float* Dtot, bf16* MIX) {
;     ...
;     { const float a0 = lbp[hd * 128 + k], a1 = lbp[512 + hd * 128 + k], a2 = lbp[1024 + hd * 128 + k]; const float mx = fmaxf(a0, fmaxf(a1, a2));
;       const float e0 = __expf(a0 - mx), e1 = __expf(a1 - mx), e2 = __expf(a2 - mx); lb = e0 / (e0 + e1 + e2); }
;     f32x4 S[8];
;     if (PC) {
; #pragma unroll
;         for (int kb = 0; kb < 8; ++kb) { S[kb] = *(const f32x4*)(Sst + (size_t)unit * 16384 + (16 * kb + li) * 128 + 16 * wave + 4 * g);
;             *(LAS v2u*)(lds + HL_S + (16 * kb + li) * RS + (16 * wave + 4 * g) * 2) = (v2u){pk2(S[kb][0], S[kb][1]), pk2(S[kb][2], S[kb][3])}; }
.LBB0_458:
	v_mov_b32_e32 v61, v216
	s_lshl_b32 s14, s58, 8
	v_ashrrev_i32_e32 v63, 6, v61
	v_and_b32_e32 v68, 15, v61
	s_and_b32 s18, s14, 0x1f00
	v_lshlrev_b32_e32 v44, 4, v63
	s_lshl_b32 s14, s58, 2
	v_or_b32_e32 v46, v44, v68
	s_and_b32 s17, s14, 0x180
	v_add_u32_e32 v0, s17, v46
	s_ashr_i32 s59, s58, 31
	s_and_b32 s5, s84, 0xffffe000
	s_and_b32 s16, s86, 0x1f00
	s_lshl_b32 s0, s58, 6
	v_ashrrev_i32_e32 v1, 31, v0
	s_lshl_b64 s[14:15], s[58:59], 16
	v_lshl_add_u64 v[20:21], v[0:1], 2, s[78:79]
	v_add_u32_e32 v0, 0x400, v0
	s_add_u32 s14, s80, s14
	v_bfe_u32 v69, v61, 4, 2
	v_ashrrev_i32_e32 v1, 31, v0
	s_addc_u32 s15, s81, s15
	v_ashrrev_i32_e32 v45, 31, v44
	v_lshl_add_u64 v[22:23], v[0:1], 2, s[78:79]
	v_lshl_add_u64 v[0:1], v[44:45], 2, s[14:15]
	v_lshlrev_b32_e32 v56, 4, v69
	v_lshlrev_b32_e32 v30, 9, v68
	v_or_b32_e32 v45, 32, v68
	v_lshl_add_u64 v[28:29], v[0:1], 0, v[56:57]
	v_mov_b32_e32 v31, v57
	v_or_b32_e32 v2, 0x2000, v30
	v_mov_b32_e32 v3, v57
	v_lshlrev_b32_e32 v8, 9, v45
	v_mov_b32_e32 v9, v57
	v_or_b32_e32 v10, 0x6000, v30
	v_mov_b32_e32 v11, v57
	v_or_b32_e32 v16, 0x8000, v30
	v_mov_b32_e32 v17, v57
	v_lshl_add_u64 v[0:1], v[28:29], 0, v[30:31]
	v_lshl_add_u64 v[2:3], v[28:29], 0, v[2:3]
	v_lshl_add_u64 v[8:9], v[28:29], 0, v[8:9]
	v_lshl_add_u64 v[10:11], v[28:29], 0, v[10:11]
	v_lshl_add_u64 v[16:17], v[28:29], 0, v[16:17]
	global_load_dwordx4 v[4:7], v[0:1], off
	s_nop 0
	global_load_dwordx4 v[0:3], v[2:3], off
	s_nop 0
	global_load_dwordx4 v[12:15], v[8:9], off
	s_nop 0
	global_load_dwordx4 v[8:11], v[10:11], off
	s_nop 0
	global_load_dwordx4 v[16:19], v[16:17], off
	s_nop 0
	global_load_dword v42, v[20:21], off
	global_load_dword v43, v[20:21], off offset:2048
	global_load_dword v47, v[22:23], off
	v_or_b32_e32 v20, 0xa000, v30
	v_mov_b32_e32 v21, v57
	v_lshl_add_u64 v[20:21], v[28:29], 0, v[20:21]
	v_or_b32_e32 v24, 0xc000, v30
	v_mov_b32_e32 v25, v57
	global_load_dwordx4 v[20:23], v[20:21], off
	v_lshl_add_u64 v[24:25], v[28:29], 0, v[24:25]
	v_or_b32_e32 v30, 0xe000, v30
	global_load_dwordx4 v[24:27], v[24:25], off
	v_lshl_add_u64 v[28:29], v[28:29], 0, v[30:31]
	global_load_dwordx4 v[28:31], v[28:29], off
	v_lshlrev_b32_e32 v70, 2, v69
	v_or_b32_e32 v32, v70, v44
	v_lshl_add_u32 v48, v32, 1, 0
	v_mad_u32_u24 v49, v68, s88, v48
	v_mad_u32_u24 v104, v68, s88, v96
	v_mad_u32_u24 v105, v68, s88, v97
	v_add_u32_e32 v50, v48, v104
	v_mad_u32_u24 v106, v68, s88, v98
	s_and_b32 s0, s0, 0xffffe000
	s_or_b32 s18, s0, s18
	s_lshl_b32 s0, s17, 2
	s_add_u32 s14, s82, s0
	s_waitcnt vmcnt(26)
	v_lshlrev_b32_e32 v73, 3, v69
	s_addc_u32 s15, s83, 0
	s_lshl_b32 s0, s17, 1
	s_waitcnt vmcnt(25)
	v_ashrrev_i32_e32 v74, 4, v61
	v_lshl_add_u32 v72, v46, 1, 0
	v_bfe_u32 v71, v61, 2, 2
	v_add_u32_e32 v112, 0, v56
	v_lshlrev_b32_e32 v66, 3, v68
	v_or_b32_e32 v121, 32, v73
	v_cmp_gt_i32_e64 s[44:45], 4, v63
	v_mul_u32_u24_e32 v103, 0x110, v68
	v_mul_u32_u24_e32 v45, 0x50, v45
	v_cmp_eq_u32_e64 s[38:39], 0, v69
	v_cmp_lt_u32_e64 s[40:41], 1, v69
	v_cmp_eq_u32_e64 s[42:43], 3, v69
	v_cmp_gt_u32_e64 s[50:51], v70, v68
	v_cmp_lt_u32_e64 s[52:53], v70, v68
	v_lshl_add_u32 v131, v121, 1, 0
	v_lshl_add_u32 v118, v68, 2, 0
	v_add_u32_e32 v131, v131, v103
	s_waitcnt vmcnt(10)
	v_cvt_pk_bf16_f32 v32, v4, v5
	v_cvt_pk_bf16_f32 v33, v6, v7
	s_waitcnt vmcnt(9)
	v_cvt_pk_bf16_f32 v34, v0, v1
	s_waitcnt vmcnt(3)
	v_max3_f32 v51, v42, v43, v47
	v_cvt_pk_bf16_f32 v35, v2, v3
	ds_write_b64 v49, v[32:33] offset:58368
	ds_write_b64 v49, v[34:35] offset:62720
	v_sub_f32_e32 v32, v42, v51
	v_sub_f32_e32 v33, v43, v51
	v_sub_f32_e32 v34, v47, v51
	v_mul_f32_e32 v32, 0x3fb8aa3b, v32
	v_mul_f32_e32 v33, 0x3fb8aa3b, v33
	v_mul_f32_e32 v34, 0x3fb8aa3b, v34
	v_exp_f32_e32 v54, v32
	v_exp_f32_e32 v32, v33
	v_exp_f32_e32 v33, v34
	v_cvt_pk_bf16_f32 v36, v12, v13
	v_cvt_pk_bf16_f32 v37, v14, v15
	v_add_f32_e32 v32, v54, v32
	v_cvt_pk_bf16_f32 v40, v16, v17
	v_cvt_pk_bf16_f32 v41, v18, v19
	v_add_f32_e32 v55, v33, v32
	v_add_u32_e32 v34, v48, v105
	s_waitcnt vmcnt(2)
	v_cvt_pk_bf16_f32 v32, v20, v21
	v_cvt_pk_bf16_f32 v33, v22, v23
	v_cvt_pk_bf16_f32 v38, v8, v9
	v_cvt_pk_bf16_f32 v39, v10, v11
	ds_write_b64 v50, v[36:37] offset:58368
	ds_write_b64 v50, v[38:39] offset:62720
	ds_write_b64 v34, v[40:41] offset:58368
	ds_write_b64 v34, v[32:33] offset:62720
	s_waitcnt vmcnt(1)
	v_cvt_pk_bf16_f32 v32, v24, v25
	v_cvt_pk_bf16_f32 v33, v26, v27
	v_add_u32_e32 v34, v48, v106
	ds_write_b64 v34, v[32:33] offset:58368
	s_waitcnt vmcnt(0)
; #define LAS __attribute__((address_space(3)))
; __device__ __forceinline__ unsigned pk2(float lo, float hi) { f32x2_t v = {lo, hi}; bf16x2_t b = __builtin_convertvector(v, bf16x2_t); return __builtin_bit_cast(unsigned, b); }
; template <bool PC> __device__ __forceinline__ void hgrn_unit(LAS unsigned char* lds, int unit, const bf16* P0, const float* lbp, const float* ong, float* Lst, const float* Sst, float* Dtot, bf16* MIX) {
;     ...
;       const float e0 = __expf(a0 - mx), e1 = __expf(a1 - mx), e2 = __expf(a2 - mx); lb = e0 / (e0 + e1 + e2); }
;     f32x4 S[8];
;     if (PC) {
; #pragma unroll
;         for (int kb = 0; kb < 8; ++kb) { S[kb] = *(const f32x4*)(Sst + (size_t)unit * 16384 + (16 * kb + li) * 128 + 16 * wave + 4 * g);
;             *(LAS v2u*)(lds + HL_S + (16 * kb + li) * RS + (16 * wave + 4 * g) * 2) = (v2u){pk2(S[kb][0], S[kb][1]), pk2(S[kb][2], S[kb][3])}; }
;     } else {
; #pragma unroll
;         for (int kb = 0; kb < 8; ++kb) S[kb] = (f32x4){0.f, 0.f, 0.f, 0.f};
;     }
;     float sumlog = 0.f;
;     f32x4 g0 = (f32x4){0.f, 0.f, 0.f, 0.f}, g1 = g0; if (PC) { g0 = *(const f32x4*)(ong + hd * 128 + 8 * (tid & 15)); g1 = *(const f32x4*)(ong + hd * 128 + 8 * (tid & 15) + 4); }
;     LAS float* DEC = (LAS float*)(lds + HL_DEC);
;     unsigned nf[8], nq[8]; v4u nv, ng = (v4u){0u, 0u, 0u, 0u};
;     ...
;     HG_LOAD(0);
	v_cvt_pk_bf16_f32 v32, v28, v29
	v_cvt_pk_bf16_f32 v33, v30, v31
	ds_write_b64 v34, v[32:33] offset:62720
	v_lshlrev_b32_e32 v36, 5, v68
	v_or_b32_e32 v40, s18, v73
	global_load_dwordx4 v[32:35], v36, s[14:15]
	s_nop 0
	global_load_dwordx4 v[36:39], v36, s[14:15] offset:16
	v_mad_i64_i32 v[40:41], s[14:15], v40, s90, v[58:59]
	v_ashrrev_i32_e32 v47, 31, v46
	v_lshl_add_u64 v[40:41], v[40:41], 0, s[0:1]
	v_lshlrev_b64 v[48:49], 1, v[46:47]
	v_lshl_add_u64 v[40:41], v[40:41], 0, v[48:49]
	s_movk_i32 s14, 0x1000
	v_add_co_u32_e32 v42, vcc, s14, v40
	s_movk_i32 s14, 0x3000
	s_nop 0
	v_addc_co_u32_e32 v43, vcc, 0, v41, vcc
	v_add_co_u32_e32 v50, vcc, s14, v40
	s_movk_i32 s14, 0x4000
	s_nop 0
	v_addc_co_u32_e32 v51, vcc, 0, v41, vcc
	v_add_co_u32_e32 v52, vcc, s14, v40
	s_movk_i32 s14, 0x7000
	s_nop 0
	v_addc_co_u32_e32 v53, vcc, 0, v41, vcc
	global_load_ushort v93, v[40:41], off offset:1024
	global_load_ushort v92, v[42:43], off offset:3072
	global_load_ushort v89, v[50:51], off offset:1024
	global_load_ushort v88, v[52:53], off offset:3072
	global_load_ushort v85, v[52:53], off offset:2048
	global_load_ushort v84, v[50:51], off
	global_load_ushort v87, v[42:43], off offset:2048
	global_load_ushort v86, v[40:41], off
	v_add_co_u32_e32 v42, vcc, s89, v40
	v_addc_co_u32_e32 v43, vcc, 0, v41, vcc
	v_add_co_u32_e32 v50, vcc, s14, v40
	s_mov_b32 s14, 0x9000
	s_nop 0
	v_addc_co_u32_e32 v51, vcc, 0, v41, vcc
	v_add_co_u32_e32 v52, vcc, s14, v40
	s_mov_b32 s14, 0xa000
	s_nop 0
	v_addc_co_u32_e32 v53, vcc, 0, v41, vcc
	v_add_co_u32_e32 v40, vcc, s14, v40
	v_div_scale_f32 v47, s[14:15], v55, v55, v54
	v_rcp_f32_e32 v60, v47
	v_addc_co_u32_e32 v41, vcc, 0, v41, vcc
	global_load_ushort v91, v[42:43], off offset:1024
	global_load_ushort v90, v[50:51], off offset:3072
	global_load_ushort v95, v[52:53], off offset:1024
	global_load_ushort v94, v[40:41], off offset:3072
	global_load_ushort v81, v[40:41], off offset:2048
	global_load_ushort v80, v[52:53], off
	global_load_ushort v83, v[50:51], off offset:2048
	global_load_ushort v82, v[42:43], off
	v_fma_f32 v40, -v47, v60, 1.0
	v_fmac_f32_e32 v60, v40, v60
	v_div_scale_f32 v40, vcc, v54, v55, v54
	v_mul_f32_e32 v41, v40, v60
	v_fma_f32 v42, -v47, v41, v40
	v_fmac_f32_e32 v41, v42, v60
	v_fma_f32 v40, -v47, v41, v40
	v_div_fmas_f32 v40, v40, v60, v41
	v_div_fixup_f32 v60, v40, v55, v54
	v_add_u32_e32 v40, s18, v74
	v_mad_i64_i32 v[40:41], s[14:15], v40, s90, v[58:59]
	v_lshl_add_u64 v[40:41], v[40:41], 0, s[0:1]
	v_lshlrev_b32_e32 v50, 4, v68
	v_mov_b32_e32 v51, v57
	v_lshl_add_u64 v[40:41], v[40:41], 0, v[50:51]
	global_load_dwordx4 v[52:55], v[40:41], off offset:2048
	s_nop 0
	global_load_dwordx4 v[40:43], v[40:41], off offset:3072
	v_mul_lo_u32 v47, v74, s88
	v_cmp_lt_i32_e32 vcc, v100, v217
	v_add_u32_e32 v75, 0, v47
	s_movk_i32 s14, 0x4e
	v_cndmask_b32_e32 v47, v100, v208, vcc
	v_cmp_lt_i32_e32 vcc, v101, v217
	v_lshlrev_b32_e32 v107, 2, v47
	v_mad_u64_u32 v[64:65], s[14:15], v46, s14, v[72:73]
	v_cndmask_b32_e32 v47, v101, v208, vcc
	v_cmp_lt_i32_e32 vcc, v102, v217
	v_lshlrev_b32_e32 v108, 2, v47
	s_movk_i32 s14, 0xffb4
	v_cndmask_b32_e32 v47, v102, v208, vcc
	v_cmp_lt_i32_e32 vcc, v211, v209
	v_lshlrev_b32_e32 v109, 2, v47
	v_mul_lo_u32 v76, v46, s14
	v_cndmask_b32_e32 v47, v208, v211, vcc
	v_cmp_lt_i32_e32 vcc, v210, v209
	v_lshlrev_b32_e32 v110, 2, v47
	v_ashrrev_i32_e32 v46, 7, v61
	v_cndmask_b32_e32 v47, v208, v210, vcc
	v_lshlrev_b32_e32 v111, 2, v47
	v_and_b32_e32 v47, 1, v63
	v_lshl_or_b32 v65, v47, 4, v68
	v_lshl_or_b32 v67, v46, 4, v68
	v_mad_u32_u24 v77, v65, s88, 0
	v_mul_lo_u32 v65, v67, s88
	s_movk_i32 s14, 0xff40
	v_cmp_le_i32_e64 s[46:47], v47, v46
	v_add_u32_e32 v65, 0, v65
	v_cmp_eq_u32_e64 s[48:49], v47, v46
	v_mul_lo_u32 v46, v67, s14
	v_lshlrev_b32_e32 v47, 5, v47
	v_add3_u32 v78, v65, v46, v47
	v_or_b32_e32 v46, v73, v71
	v_mul_u32_u24_e32 v79, 0x110, v46
	v_mad_u32_u24 v127, v46, s88, 0
	v_lshlrev_b32_e32 v46, 2, v61
	v_and_or_b32 v46, v46, 12, v44
	v_lshlrev_b32_e32 v128, 1, v46
	v_sub_u32_e32 v46, v112, v73
	s_movk_i32 s14, 0x84
	v_lshl_add_u32 v113, v63, 5, v46
	v_mul_lo_u32 v46, v74, s14
	v_cmp_lt_i32_e32 vcc, v215, v209
	v_add_lshl_u32 v138, v46, v66, 2
	v_or_b32_e32 v61, v121, v71
	v_cndmask_b32_e32 v46, v208, v215, vcc
	v_cmp_lt_i32_e32 vcc, v214, v209
	v_lshlrev_b32_e32 v114, 2, v46
	v_mul_u32_u24_e32 v130, 0x110, v61
	v_cndmask_b32_e32 v46, v208, v214, vcc
	v_cmp_lt_i32_e32 vcc, v213, v209
	v_lshlrev_b32_e32 v115, 2, v46
	v_or_b32_e32 v61, 64, v73
	v_cndmask_b32_e32 v46, v208, v213, vcc
	v_cmp_lt_i32_e32 vcc, v212, v209
	v_lshlrev_b32_e32 v116, 2, v46
	v_mov_b32_e32 v47, v57
	v_cndmask_b32_e32 v46, v208, v212, vcc
	v_lshlrev_b32_e32 v117, 2, v46
	v_or_b32_e32 v46, s17, v66
	v_lshlrev_b32_e32 v46, 1, v46
	v_or_b32_e32 v63, v61, v71
	v_lshl_add_u32 v133, v61, 1, 0
	v_or_b32_e32 v61, 0x60, v73
	v_lshl_add_u64 v[66:67], s[2:3], 0, v[46:47]
	v_or_b32_e32 v47, 2, v70
	v_mul_u32_u24_e32 v132, 0x110, v63
	v_or_b32_e32 v63, v61, v71
	v_lshl_add_u32 v136, v61, 1, 0
	v_mul_u32_u24_e32 v61, 0x84, v68
	v_cmp_gt_u32_e64 s[54:55], v47, v68
	v_or_b32_e32 v47, 3, v70
	v_add_lshl_u32 v119, v61, v44, 2
	s_add_u32 s14, s20, s0
	v_add_u32_e32 v134, 0, v128
	v_mul_u32_u24_e32 v46, 0x880, v69
	v_cmp_gt_u32_e64 s[56:57], v47, v68
	v_mul_u32_u24_e32 v47, 0x50, v68
	v_mul_u32_u24_e32 v135, 0x110, v63
	v_add_u32_e32 v44, 0x2100, v119
	s_addc_u32 s15, s21, 0
	v_sub_f32_e32 v62, 1.0, v60
	v_lshl_add_u64 v[68:69], s[14:15], 0, v[48:49]
	v_lshl_add_u64 v[70:71], s[14:15], 0, v[50:51]
	s_or_b32 s0, s5, s16
	v_add_u32_e32 v122, v75, v50
	v_add_u32_e32 v123, v72, v46
	v_add_u32_e32 v127, v127, v128
	v_add_u32_e32 v128, v112, v47
	v_add_u32_e32 v129, v134, v79
	v_add_u32_e32 v130, v134, v130
	v_add_u32_e32 v132, v134, v132
	v_add_u32_e32 v134, v134, v135
	v_add_u32_e32 v135, v136, v103
	v_add_u32_e32 v136, v112, v45
	v_add_u32_e32 v137, v112, v44
	s_waitcnt vmcnt(0)
	v_mov_b32_e32 v139, v93
	v_mov_b64_e32 v[46:47], v[42:43]
	v_mov_b64_e32 v[48:49], v[52:53]
	v_mov_b32_e32 v61, v60
	v_mov_b32_e32 v63, v62
	v_add_u32_e32 v120, s0, v74
	v_or_b32_e32 v121, s0, v121
	v_add_u32_e32 v124, v64, v76
	v_add_u32_e32 v125, v77, v56
	v_add_u32_e32 v126, v78, v73
	v_add_u32_e32 v133, v133, v103
	v_add_u32_e32 v138, 0, v138
	s_mov_b32 s0, 0
	v_mov_b32_e32 v140, v92
	v_mov_b32_e32 v141, v89
	v_mov_b32_e32 v142, v88
	v_mov_b32_e32 v143, v91
	v_mov_b32_e32 v144, v90
	v_mov_b32_e32 v145, v95
	v_mov_b32_e32 v146, v94
	v_mov_b64_e32 v[44:45], v[40:41]
	v_mov_b64_e32 v[50:51], v[54:55]
	v_mov_b64_e32 v[74:75], v[86:87]
	v_mov_b64_e32 v[72:73], v[84:85]
	v_mov_b64_e32 v[78:79], v[82:83]
	v_mov_b64_e32 v[76:77], v[80:81]
	s_branch .LBB0_462

; #define LAS __attribute__((address_space(3)))
; template <bool PC> __device__ __forceinline__ void hgrn_unit(LAS unsigned char* lds, int unit, const bf16* P0, const float* lbp, const float* ong, float* Lst, const float* Sst, float* Dtot, bf16* MIX) {
;     ...
;         const bf16x8 xv = trfrag((const LAS char*)(lds + HL_V + (8 * g + q4) * RS + (16 * wave + 4 * p4) * 2), 4 * RS);
;         bf16x8 xs[4], yq[2][4], ysc[2], yk[8]; float dcv[8];
;         if (PC) {
; #pragma unroll
;             for (int tb = 0; tb < 2; ++tb) ysc[tb] = *(const LAS bf16x8*)(lds + HL_SC + (16 * tb + li) * 80 + g * 16);
; #pragma unroll
;             for (int ks = 0; ks < 4; ++ks) { xs[ks] = trfrag((const LAS char*)(lds + HL_S + (32 * ks + 8 * g + q4) * RS + (16 * wave + 4 * p4) * 2), 4 * RS);
; #pragma unroll
;                 for (int tb = 0; tb < 2; ++tb) yq[tb][ks] = *(const LAS bf16x8*)(lds + HL_QT + (16 * tb + li) * RS + (32 * ks + 8 * g) * 2); }
;         }
; #pragma unroll
;         for (int kb = 0; kb < 8; ++kb) { dcv[kb] = DEC[16 * kb + li]; yk[kb] = *(const LAS bf16x8*)(lds + HL_KE + (16 * kb + li) * 80 + g * 16); }
;         __builtin_amdgcn_sched_barrier(0);
;         if (PC) {
;             f32x4 o[2];
; #pragma unroll
;             for (int tb = 0; tb < 2; ++tb) o[tb] = __builtin_amdgcn_mfma_f32_16x16x32_bf16(xv, ysc[tb], (f32x4){0.f, 0.f, 0.f, 0.f}, 0, 0, 0);
; #pragma unroll
;             for (int ks = 0; ks < 4; ++ks)
; #pragma unroll
;                 for (int tb = 0; tb < 2; ++tb) o[tb] = __builtin_amdgcn_mfma_f32_16x16x32_bf16(xs[ks], yq[tb][ks], o[tb], 0, 0, 0);
; #pragma unroll
;             for (int tb = 0; tb < 2; ++tb) *(LAS f32x4*)(lds + HL_OUT + ((16 * tb + li) * 132 + 16 * wave + 4 * g) * 4) = o[tb];
;         }
; #pragma unroll
;         for (int kb = 0; kb < 8; ++kb) S[kb] = __builtin_amdgcn_mfma_f32_16x16x32_bf16(xv, yk[kb], S[kb] * dcv[kb], 0, 0, 0);
.LBB0_461:
	s_or_b64 exec, exec, s[18:19]
	s_waitcnt lgkmcnt(0)
	s_barrier
	v_add_u32_e32 v147, v112, v103
	ds_read_b64_tr_b16 v[52:53], v127
	ds_read_b64_tr_b16 v[54:55], v127 offset:1088
	ds_read_b128 v[80:83], v128 offset:36352
	ds_read_b128 v[84:87], v128 offset:37632
	ds_read_b64_tr_b16 v[88:89], v129 offset:58368
	ds_read_b64_tr_b16 v[90:91], v129 offset:59456
	ds_read_b128 v[92:95], v147 offset:8704
	ds_read_b128 v[148:151], v147 offset:13056
	ds_read_b64_tr_b16 v[152:153], v130 offset:58368
	ds_read_b64_tr_b16 v[154:155], v130 offset:59456
	ds_read_b128 v[156:159], v131 offset:8704
	ds_read_b128 v[160:163], v131 offset:13056
	ds_read_b64_tr_b16 v[164:165], v132 offset:58368
	ds_read_b64_tr_b16 v[166:167], v132 offset:59456
	ds_read_b128 v[168:171], v133 offset:8704
	ds_read_b128 v[172:175], v133 offset:13056
	ds_read_b64_tr_b16 v[176:177], v134 offset:58368
	ds_read_b64_tr_b16 v[178:179], v134 offset:59456
	ds_read_b128 v[180:183], v135 offset:8704
	ds_read_b128 v[184:187], v135 offset:13056
	v_add_u32_e32 v147, 0xa000, v118
	ds_read2_b32 v[230:231], v147 offset1:16
	ds_read_b128 v[188:191], v128 offset:26112
	ds_read_b128 v[192:195], v128 offset:27392
	ds_read2_b32 v[232:233], v147 offset0:32 offset1:48
	ds_read_b128 v[196:199], v136 offset:26112
	ds_read_b128 v[200:203], v136 offset:27392
	ds_read2_b32 v[234:235], v147 offset0:64 offset1:80
	ds_read_b128 v[204:207], v136 offset:28672
	ds_read_b128 v[218:221], v136 offset:29952
	ds_read2_b32 v[236:237], v147 offset0:96 offset1:112
	ds_read_b128 v[222:225], v136 offset:31232
	ds_read_b128 v[226:229], v136 offset:32512
	s_waitcnt lgkmcnt(14)
	v_mfma_f32_16x16x32_bf16 v[80:83], v[52:55], v[80:83], 0
	s_waitcnt lgkmcnt(11)
	v_pk_mul_f32 v[6:7], v[6:7], v[230:231] op_sel_hi:[1,0]
	v_pk_mul_f32 v[4:5], v[4:5], v[230:231] op_sel_hi:[1,0]
	s_waitcnt lgkmcnt(8)
	v_pk_mul_f32 v[14:15], v[14:15], v[232:233] op_sel_hi:[1,0]
	v_mfma_f32_16x16x32_bf16 v[84:87], v[52:55], v[84:87], 0
	v_mul_f32_e64 v12, v12, v232
	v_mul_f32_e64 v13, v13, v232
	s_waitcnt lgkmcnt(5)
	v_pk_mul_f32 v[18:19], v[18:19], v[234:235] op_sel_hi:[1,0]
	v_pk_mul_f32 v[16:17], v[16:17], v[234:235] op_sel_hi:[1,0]
	v_mfma_f32_16x16x32_bf16 v[80:83], v[88:91], v[92:95], v[80:83]
	s_waitcnt lgkmcnt(2)
	v_pk_mul_f32 v[26:27], v[26:27], v[236:237] op_sel_hi:[1,0]
	v_pk_mul_f32 v[24:25], v[24:25], v[236:237] op_sel_hi:[1,0]
	s_waitcnt vmcnt(17)
	v_mov_b32_e32 v93, v139
	v_mfma_f32_16x16x32_bf16 v[84:87], v[88:91], v[148:151], v[84:87]
	v_add_u32_e32 v88, v112, v119
	s_waitcnt vmcnt(16)
	v_mov_b32_e32 v92, v140
	s_waitcnt vmcnt(7)
	v_mov_b32_e32 v95, v145
	v_mfma_f32_16x16x32_bf16 v[80:83], v[152:155], v[156:159], v[80:83]
	s_waitcnt vmcnt(6)
	v_mov_b32_e32 v94, v146
	v_mfma_f32_16x16x32_bf16 v[84:87], v[152:155], v[160:163], v[84:87]
	v_mfma_f32_16x16x32_bf16 v[80:83], v[164:167], v[168:171], v[80:83]
	v_mfma_f32_16x16x32_bf16 v[84:87], v[164:167], v[172:175], v[84:87]
	v_mfma_f32_16x16x32_bf16 v[80:83], v[176:179], v[180:183], v[80:83]
	v_mfma_f32_16x16x32_bf16 v[4:7], v[52:55], v[188:191], v[4:7]
	v_mfma_f32_16x16x32_bf16 v[12:15], v[52:55], v[196:199], v[12:15]
	s_nop 5
	ds_write_b128 v88, v[80:83] offset:41472
	v_mfma_f32_16x16x32_bf16 v[80:83], v[176:179], v[184:187], v[84:87]
	v_mfma_f32_16x16x32_bf16 v[16:19], v[52:55], v[204:207], v[16:19]
	s_waitcnt lgkmcnt(2)
	v_mfma_f32_16x16x32_bf16 v[24:27], v[52:55], v[222:225], v[24:27]
	s_nop 4
	ds_write_b128 v137, v[80:83] offset:41472
	v_mov_b32_e32 v80, v231
	v_pk_mul_f32 v[2:3], v[2:3], v[80:81] op_sel_hi:[1,0]
	v_pk_mul_f32 v[0:1], v[0:1], v[80:81] op_sel_hi:[1,0]
	v_mov_b32_e32 v80, v233
	v_pk_mul_f32 v[10:11], v[10:11], v[80:81] op_sel_hi:[1,0]
	v_mfma_f32_16x16x32_bf16 v[0:3], v[52:55], v[192:195], v[0:3]
	v_mul_f32_e64 v8, v8, v80
	v_mul_f32_e64 v9, v9, v80
	v_mov_b32_e32 v80, v235
	v_pk_mul_f32 v[22:23], v[22:23], v[80:81] op_sel_hi:[1,0]
	v_pk_mul_f32 v[20:21], v[20:21], v[80:81] op_sel_hi:[1,0]
	v_mov_b32_e32 v80, v237
	v_mfma_f32_16x16x32_bf16 v[8:11], v[52:55], v[200:203], v[8:11]
	v_mul_f32_e64 v30, v30, v80
	v_mul_f32_e64 v31, v31, v80
	v_pk_mul_f32 v[28:29], v[28:29], v[80:81] op_sel_hi:[1,0]
	v_cvt_pk_bf16_f32 v80, v4, v5
	v_cvt_pk_bf16_f32 v81, v6, v7
	v_add_u32_e32 v82, v113, v103
	s_waitcnt lgkmcnt(0)
	s_barrier
; #define LAS __attribute__((address_space(3)))
; __device__ __forceinline__ unsigned pk2(float lo, float hi) { f32x2_t v = {lo, hi}; bf16x2_t b = __builtin_convertvector(v, bf16x2_t); return __builtin_bit_cast(unsigned, b); }
; __device__ __forceinline__ float bflo(unsigned w) { return __uint_as_float(w << 16); }
; __device__ __forceinline__ float bfhi(unsigned w) { return __uint_as_float(w & 0xffff0000u); }
; __device__ __forceinline__ float siluf(float x) { return x * sigmf(x); }
; template <bool PC> __device__ __forceinline__ void hgrn_unit(LAS unsigned char* lds, int unit, const bf16* P0, const float* lbp, const float* ong, float* Lst, const float* Sst, float* Dtot, bf16* MIX) {
;     ...
;         if (PC) {
; #pragma unroll
;             for (int kb = 0; kb < 8; ++kb) *(LAS v2u*)(lds + HL_S + (16 * kb + li) * RS + (16 * wave + 4 * g) * 2) = (v2u){pk2(S[kb][0], S[kb][1]), pk2(S[kb][2], S[kb][3])};
;             const int t = tid >> 4, vg = tid & 15;
;             const f32x4 o0 = *(const LAS f32x4*)(lds + HL_OUT + (t * 132 + 8 * vg) * 4), o1 = *(const LAS f32x4*)(lds + HL_OUT + (t * 132 + 8 * vg + 4) * 4);
;             float ss = (o0[0] * o0[0] + o0[1] * o0[1]) + (o0[2] * o0[2] + o0[3] * o0[3]) + (o1[0] * o1[0] + o1[1] * o1[1]) + (o1[2] * o1[2] + o1[3] * o1[3]);
;             ss += __shfl_xor(ss, 1); ss += __shfl_xor(ss, 2); ss += __shfl_xor(ss, 4); ss += __shfl_xor(ss, 8);
;             const float rstd = __builtin_amdgcn_rsqf(ss * (1.f / 128.f) + EPSN);
;             const int col = hd * 128 + 8 * vg;
;             v4u w;
;             w[0] = pk2(o0[0] * rstd * g0[0] * siluf(bflo(ga[0])), o0[1] * rstd * g0[1] * siluf(bfhi(ga[0])));
;             w[1] = pk2(o0[2] * rstd * g0[2] * siluf(bflo(ga[1])), o0[3] * rstd * g0[3] * siluf(bfhi(ga[1])));
;             w[2] = pk2(o1[0] * rstd * g1[0] * siluf(bflo(ga[2])), o1[1] * rstd * g1[1] * siluf(bfhi(ga[2])));
;             w[3] = pk2(o1[2] * rstd * g1[2] * siluf(bflo(ga[3])), o1[3] * rstd * g1[3] * siluf(bfhi(ga[3])));
;             *(v4u*)(MIX + (size_t)(r0 + t) * D + col) = w;
	ds_write_b64 v82, v[80:81] offset:58368
	v_cvt_pk_bf16_f32 v80, v0, v1
	v_cvt_pk_bf16_f32 v81, v2, v3
	v_mfma_f32_16x16x32_bf16 v[20:23], v[52:55], v[218:221], v[20:23]
	ds_write_b64 v82, v[80:81] offset:62720
	v_cvt_pk_bf16_f32 v80, v12, v13
	v_cvt_pk_bf16_f32 v81, v14, v15
	v_add_u32_e32 v82, v113, v104
	s_waitcnt lgkmcnt(4)
	v_mfma_f32_16x16x32_bf16 v[28:31], v[52:55], v[226:229], v[28:31]
	ds_write_b64 v82, v[80:81] offset:58368
	v_cvt_pk_bf16_f32 v80, v8, v9
	v_cvt_pk_bf16_f32 v81, v10, v11
	ds_write_b64 v82, v[80:81] offset:62720
	v_cvt_pk_bf16_f32 v80, v16, v17
	v_cvt_pk_bf16_f32 v81, v18, v19
	v_add_u32_e32 v82, v113, v105
	ds_write_b64 v82, v[80:81] offset:58368
	v_cvt_pk_bf16_f32 v80, v20, v21
	v_cvt_pk_bf16_f32 v81, v22, v23
	ds_write_b64 v82, v[80:81] offset:62720
	v_cvt_pk_bf16_f32 v80, v24, v25
	v_cvt_pk_bf16_f32 v81, v26, v27
	v_add_u32_e32 v82, v113, v106
	v_cvt_pk_bf16_f32 v52, v28, v29
	v_cvt_pk_bf16_f32 v53, v30, v31
	ds_write_b64 v82, v[80:81] offset:58368
	ds_write_b64 v82, v[52:53] offset:62720
	ds_read_b128 v[52:55], v138 offset:41472
	ds_read_b128 v[80:83], v138 offset:41488
	s_waitcnt lgkmcnt(1)
	v_pk_mul_f32 v[84:85], v[54:55], v[54:55]
	v_pk_mul_f32 v[86:87], v[52:53], v[52:53]
	s_nop 0
	v_pk_mov_b32 v[88:89], v[86:87], v[84:85] op_sel:[1,0]
	v_mov_b32_e32 v87, v85
	v_pk_add_f32 v[84:85], v[88:89], v[86:87]
	s_waitcnt lgkmcnt(0)
	v_pk_mul_f32 v[86:87], v[82:83], v[82:83]
	v_pk_mul_f32 v[88:89], v[80:81], v[80:81]
	v_mov_b32_e32 v90, v86
	v_mov_b32_e32 v91, v88
	v_mov_b32_e32 v88, v87
	v_pk_add_f32 v[86:87], v[90:91], v[88:89]
	v_add_f32_e32 v84, v84, v85
	v_add_f32_e32 v84, v84, v87
	v_add_f32_e32 v84, v86, v84
	v_mov_b32_e32 v91, v143
	s_waitcnt lgkmcnt(0)
	v_add_f32_dpp v84, v84, v84 quad_perm:[1,0,3,2] row_mask:0xf bank_mask:0xf
	s_nop 1
	v_add_f32_dpp v84, v84, v84 quad_perm:[2,3,0,1] row_mask:0xf bank_mask:0xf
	s_nop 1
	v_add_f32_dpp v84, v84, v84 row_half_mirror row_mask:0xf bank_mask:0xf
	s_nop 1
	v_add_f32_dpp v84, v84, v84 row_mirror row_mask:0xf bank_mask:0xf
	s_nop 1
	v_fmamk_f32 v86, v84, 0x3c000000, v99
	v_lshlrev_b32_e32 v84, 16, v40
	v_and_b32_e32 v85, 0xffff0000, v40
	v_mul_f32_e32 v40, 0xbfb8aa3b, v84
	v_exp_f32_e32 v40, v40
	v_mul_f32_e32 v87, 0xbfb8aa3b, v85
	v_exp_f32_e32 v87, v87
	v_rsq_f32_e32 v86, v86
	v_add_f32_e32 v40, 1.0, v40
	v_rcp_f32_e32 v88, v40
	v_add_f32_e32 v40, 1.0, v87
	v_rcp_f32_e32 v89, v40
	v_pk_mul_f32 v[52:53], v[52:53], v[86:87] op_sel_hi:[1,0]
	v_pk_mul_f32 v[84:85], v[88:89], v[84:85]
	v_lshlrev_b32_e32 v88, 16, v41
	v_and_b32_e32 v89, 0xffff0000, v41
	v_mul_f32_e32 v40, 0xbfb8aa3b, v88
	v_exp_f32_e32 v87, v40
	v_mul_f32_e32 v40, 0xbfb8aa3b, v89
	v_exp_f32_e32 v90, v40
	v_pk_mul_f32 v[52:53], v[32:33], v[52:53]
	v_pk_mul_f32 v[54:55], v[54:55], v[86:87] op_sel_hi:[1,0]
	v_pk_mul_f32 v[40:41], v[84:85], v[52:53]
	v_lshlrev_b32_e32 v84, 16, v42
	v_add_f32_e32 v52, 1.0, v87
	v_add_f32_e32 v53, 1.0, v90
	v_cvt_pk_bf16_f32 v40, v40, v41
	v_and_b32_e32 v85, 0xffff0000, v42
	v_mul_f32_e32 v41, 0xbfb8aa3b, v84
	v_rcp_f32_e32 v52, v52
	v_rcp_f32_e32 v53, v53
	v_exp_f32_e32 v41, v41
	v_mul_f32_e32 v42, 0xbfb8aa3b, v85
	v_exp_f32_e32 v42, v42
	v_pk_mul_f32 v[54:55], v[34:35], v[54:55]
	v_pk_mul_f32 v[52:53], v[52:53], v[88:89]
	v_add_f32_e32 v41, 1.0, v41
	v_pk_mul_f32 v[52:53], v[52:53], v[54:55]
	v_rcp_f32_e32 v54, v41
	v_add_f32_e32 v41, 1.0, v42
	v_rcp_f32_e32 v55, v41
	v_cvt_pk_bf16_f32 v41, v52, v53
	v_pk_mul_f32 v[52:53], v[80:81], v[86:87] op_sel_hi:[1,0]
	v_lshlrev_b32_e32 v80, 16, v43
	v_and_b32_e32 v81, 0xffff0000, v43
	v_mul_f32_e32 v42, 0xbfb8aa3b, v80
	v_pk_mul_f32 v[54:55], v[54:55], v[84:85]
	v_exp_f32_e32 v84, v42
	v_mul_f32_e32 v42, 0xbfb8aa3b, v81
	v_exp_f32_e32 v85, v42
	v_pk_mul_f32 v[52:53], v[36:37], v[52:53]
	v_mov_b32_e32 v89, v141
	v_pk_mul_f32 v[42:43], v[54:55], v[52:53]
	v_add_f32_e32 v52, 1.0, v84
	v_add_f32_e32 v53, 1.0, v85
	v_rcp_f32_e32 v52, v52
	v_rcp_f32_e32 v53, v53
	v_pk_mul_f32 v[54:55], v[82:83], v[86:87] op_sel_hi:[1,0]
	v_cvt_pk_bf16_f32 v42, v42, v43
	v_pk_mul_f32 v[54:55], v[38:39], v[54:55]
	v_pk_mul_f32 v[52:53], v[52:53], v[80:81]
	v_mov_b32_e32 v88, v142
	v_pk_mul_f32 v[52:53], v[52:53], v[54:55]
	v_mov_b32_e32 v90, v144
	v_cvt_pk_bf16_f32 v43, v52, v53
	v_add_u32_e32 v52, s0, v120
	v_ashrrev_i32_e32 v53, 31, v52
	v_lshlrev_b64 v[52:53], 11, v[52:53]
	v_lshl_add_u64 v[52:53], v[66:67], 0, v[52:53]
	global_store_dwordx4 v[52:53], v[40:43], off
	s_add_i32 s0, s0, 32
	s_waitcnt vmcnt(2)
	v_mov_b64_e32 v[54:55], v[50:51]
	s_waitcnt vmcnt(1)
	v_mov_b64_e32 v[40:41], v[44:45]
	s_cmpk_lg_i32 s0, 0x100
	v_mov_b64_e32 v[52:53], v[48:49]
	v_mov_b64_e32 v[42:43], v[46:47]
	v_mov_b64_e32 v[86:87], v[74:75]
	v_mov_b64_e32 v[84:85], v[72:73]
	v_mov_b64_e32 v[82:83], v[78:79]
	v_mov_b64_e32 v[80:81], v[76:77]
	s_cbranch_scc0 .LBB0_457
